# baseline (speedup 1.0000x reference)
; #define WAIT_V(n) asm volatile("s_waitcnt vmcnt(" #n ")" ::: "memory")
; #define WAIT_L(n) asm volatile("s_waitcnt lgkmcnt(" #n ")" ::: "memory")
; #define BAR __builtin_amdgcn_s_barrier()
; #define SCHED __builtin_amdgcn_sched_barrier(0)
; __device__ __forceinline__ void gemm_tile(const u16* __restrict__ A, const u16* __restrict__ Bt, const int K,
;                                           const int brow, const int bcol, f32x4 (&acc)[2][2][4][2],
;                                           const bool ZERO_INIT = true) {
;     ...
;   for (int t = 0; t < nt - 2; t += 2) {
;     LDB(B0, 0, 0); SCHED; LDA(At, 0, 0); STAGE(SA(1, 1), A, brow + HALF, t + 1);
;     WAIT_L(8); BAR; WAIT_L(0); MMA(0, 0, At, B0); BAR; SCHED;
;     LDB(B1, 0, 1); STAGE(SB(0, 0), Bt, bcol, t + 2);
;     BAR; WAIT_L(0); MMA(0, 1, At, B1); BAR;
;     LDA(At, 0, 1); STAGE(SA(0, 0), A, brow, t + 2);
;     BAR; WAIT_L(0); MMA(1, 0, At, B0); BAR; SCHED;
;     STAGE(SB(0, 1), Bt, bcol + HALF, t + 2);
;     WAIT_V(6); BAR; MMA(1, 1, At, B1); BAR;
;     LDB(B0, 1, 0); SCHED; LDA(At, 1, 0); STAGE(SA(0, 1), A, brow + HALF, t + 2);
;     WAIT_L(8); BAR; WAIT_L(0); MMA(0, 0, At, B0); BAR; SCHED;
.LBB0_164:
	ds_read_b128 v[150:153], v149
	ds_read_b128 v[154:157], v149 offset:1024
	ds_read_b128 v[158:161], v149 offset:2048
	ds_read_b128 v[162:165], v149 offset:3072
	v_lshl_add_u64 v[216:217], s[70:71], 0, v[136:137]
	s_mov_b32 m0, s83
	v_lshl_add_u64 v[200:201], v[216:217], 0, s[16:17]
	v_lshl_add_u64 v[218:219], s[70:71], 0, v[138:139]
	ds_read_b128 v[166:169], v145
	ds_read_b128 v[170:173], v145 offset:1024
	ds_read_b128 v[174:177], v143
	ds_read_b128 v[178:181], v143 offset:1024
	ds_read_b128 v[182:185], v142
	ds_read_b128 v[186:189], v142 offset:1024
	ds_read_b128 v[190:193], v141
	ds_read_b128 v[196:199], v141 offset:1024
	global_load_lds_dwordx4 v[200:201], off
	v_lshl_add_u64 v[200:201], v[218:219], 0, s[16:17]
	s_mov_b32 m0, s76
	s_nop 0
	global_load_lds_dwordx4 v[200:201], off
	s_waitcnt lgkmcnt(8)
	s_barrier
	s_waitcnt lgkmcnt(0)
	s_setprio 1
	s_waitcnt lgkmcnt(0)
	v_mfma_f32_16x16x32_bf16 v[124:127], v[166:169], v[150:153], v[124:127]
	v_mfma_f32_16x16x32_bf16 v[120:123], v[166:169], v[158:161], v[120:123]
	v_mfma_f32_16x16x32_bf16 v[116:119], v[174:177], v[150:153], v[116:119]
	v_mfma_f32_16x16x32_bf16 v[112:115], v[174:177], v[158:161], v[112:115]
	v_mfma_f32_16x16x32_bf16 v[108:111], v[182:185], v[150:153], v[108:111]
	v_mfma_f32_16x16x32_bf16 v[104:107], v[182:185], v[158:161], v[104:107]
	v_mfma_f32_16x16x32_bf16 v[100:103], v[190:193], v[150:153], v[100:103]
	v_mfma_f32_16x16x32_bf16 v[96:99], v[190:193], v[158:161], v[96:99]
	v_mfma_f32_16x16x32_bf16 v[124:127], v[170:173], v[154:157], v[124:127]
	v_mfma_f32_16x16x32_bf16 v[120:123], v[170:173], v[162:165], v[120:123]
	v_mfma_f32_16x16x32_bf16 v[116:119], v[178:181], v[154:157], v[116:119]
	v_mfma_f32_16x16x32_bf16 v[112:115], v[178:181], v[162:165], v[112:115]
	v_mfma_f32_16x16x32_bf16 v[108:111], v[186:189], v[154:157], v[108:111]
	v_mfma_f32_16x16x32_bf16 v[104:107], v[186:189], v[162:165], v[104:107]
	v_mfma_f32_16x16x32_bf16 v[100:103], v[196:199], v[154:157], v[100:103]
	v_mfma_f32_16x16x32_bf16 v[96:99], v[196:199], v[162:165], v[96:99]
	s_setprio 0
	s_barrier
	v_lshl_add_u64 v[220:221], s[70:71], 0, v[132:133]
	s_mov_b32 m0, s73
	v_lshl_add_u64 v[222:223], v[220:221], 0, s[18:19]
	ds_read_b128 v[200:203], v148
	ds_read_b128 v[204:207], v148 offset:1024
	ds_read_b128 v[208:211], v148 offset:2048
	ds_read_b128 v[212:215], v148 offset:3072
	global_load_lds_dwordx4 v[222:223], off
	v_lshl_add_u64 v[222:223], s[70:71], 0, v[134:135]
	v_lshl_add_u64 v[224:225], v[222:223], 0, s[18:19]
	s_mov_b32 m0, s96
	s_nop 0
	global_load_lds_dwordx4 v[224:225], off
	s_barrier
	s_waitcnt lgkmcnt(0)
	s_setprio 1
	s_waitcnt lgkmcnt(0)
	v_mfma_f32_16x16x32_bf16 v[92:95], v[166:169], v[200:203], v[92:95]
	v_mfma_f32_16x16x32_bf16 v[88:91], v[166:169], v[208:211], v[88:91]
	v_mfma_f32_16x16x32_bf16 v[84:87], v[174:177], v[200:203], v[84:87]
	v_mfma_f32_16x16x32_bf16 v[80:83], v[174:177], v[208:211], v[80:83]
	v_mfma_f32_16x16x32_bf16 v[76:79], v[182:185], v[200:203], v[76:79]
	v_mfma_f32_16x16x32_bf16 v[72:75], v[182:185], v[208:211], v[72:75]
	v_mfma_f32_16x16x32_bf16 v[68:71], v[190:193], v[200:203], v[68:71]
	v_mfma_f32_16x16x32_bf16 v[64:67], v[190:193], v[208:211], v[64:67]
	v_mfma_f32_16x16x32_bf16 v[92:95], v[170:173], v[204:207], v[92:95]
	v_mfma_f32_16x16x32_bf16 v[88:91], v[170:173], v[212:215], v[88:91]
	v_mfma_f32_16x16x32_bf16 v[84:87], v[178:181], v[204:207], v[84:87]
	v_mfma_f32_16x16x32_bf16 v[80:83], v[178:181], v[212:215], v[80:83]
	v_mfma_f32_16x16x32_bf16 v[76:79], v[186:189], v[204:207], v[76:79]
	v_mfma_f32_16x16x32_bf16 v[72:75], v[186:189], v[212:215], v[72:75]
	v_mfma_f32_16x16x32_bf16 v[68:71], v[196:199], v[204:207], v[68:71]
	v_mfma_f32_16x16x32_bf16 v[64:67], v[196:199], v[212:215], v[64:67]
	s_setprio 0
	s_mov_b32 m0, s95
	v_lshl_add_u64 v[224:225], v[216:217], 0, s[20:21]
	s_barrier
	ds_read_b128 v[166:169], v145 offset:16384
	ds_read_b128 v[170:173], v145 offset:17408
	ds_read_b128 v[174:177], v143 offset:16384
	ds_read_b128 v[178:181], v143 offset:17408
	ds_read_b128 v[182:185], v142 offset:16384
	ds_read_b128 v[186:189], v142 offset:17408
	ds_read_b128 v[190:193], v141 offset:16384
	ds_read_b128 v[196:199], v141 offset:17408
	global_load_lds_dwordx4 v[224:225], off
	v_lshl_add_u64 v[224:225], v[218:219], 0, s[20:21]
	s_mov_b32 m0, s7
	s_nop 0
	global_load_lds_dwordx4 v[224:225], off
	s_barrier
	s_waitcnt lgkmcnt(0)
	s_setprio 1
	s_waitcnt lgkmcnt(0)
	v_mfma_f32_16x16x32_bf16 v[60:63], v[166:169], v[150:153], v[60:63]
	v_mfma_f32_16x16x32_bf16 v[56:59], v[166:169], v[158:161], v[56:59]
	v_mfma_f32_16x16x32_bf16 v[52:55], v[174:177], v[150:153], v[52:55]
	v_mfma_f32_16x16x32_bf16 v[48:51], v[174:177], v[158:161], v[48:51]
	v_mfma_f32_16x16x32_bf16 v[44:47], v[182:185], v[150:153], v[44:47]
	v_mfma_f32_16x16x32_bf16 v[40:43], v[182:185], v[158:161], v[40:43]
	v_mfma_f32_16x16x32_bf16 v[36:39], v[190:193], v[150:153], v[36:39]
	v_mfma_f32_16x16x32_bf16 v[32:35], v[190:193], v[158:161], v[32:35]
	v_mfma_f32_16x16x32_bf16 v[60:63], v[170:173], v[154:157], v[60:63]
	v_mfma_f32_16x16x32_bf16 v[56:59], v[170:173], v[162:165], v[56:59]
	v_mfma_f32_16x16x32_bf16 v[52:55], v[178:181], v[154:157], v[52:55]
	v_mfma_f32_16x16x32_bf16 v[48:51], v[178:181], v[162:165], v[48:51]
	v_mfma_f32_16x16x32_bf16 v[44:47], v[186:189], v[154:157], v[44:47]
	v_mfma_f32_16x16x32_bf16 v[40:43], v[186:189], v[162:165], v[40:43]
	v_mfma_f32_16x16x32_bf16 v[36:39], v[196:199], v[154:157], v[36:39]
	v_mfma_f32_16x16x32_bf16 v[32:35], v[196:199], v[162:165], v[32:35]
	s_setprio 0
	s_barrier
; #define WAIT_V(n) asm volatile("s_waitcnt vmcnt(" #n ")" ::: "memory")
; #define WAIT_L(n) asm volatile("s_waitcnt lgkmcnt(" #n ")" ::: "memory")
; #define BAR __builtin_amdgcn_s_barrier()
; #define SCHED __builtin_amdgcn_sched_barrier(0)
; __device__ __forceinline__ void gemm_tile(const u16* __restrict__ A, const u16* __restrict__ Bt, const int K,
;                                           const int brow, const int bcol, f32x4 (&acc)[2][2][4][2],
;                                           const bool ZERO_INIT = true) {
;     ...
;     STAGE(SB(0, 1), Bt, bcol + HALF, t + 2);
;     WAIT_V(6); BAR; MMA(1, 1, At, B1); BAR;
;     LDB(B0, 1, 0); SCHED; LDA(At, 1, 0); STAGE(SA(0, 1), A, brow + HALF, t + 2);
;     WAIT_L(8); BAR; WAIT_L(0); MMA(0, 0, At, B0); BAR; SCHED;
;     LDB(B1, 1, 1); STAGE(SB(1, 0), Bt, bcol, t + 3);
;     BAR; WAIT_L(0); MMA(0, 1, At, B1); BAR;
;     LDA(At, 1, 1); STAGE(SA(1, 0), A, brow, t + 3);
;     BAR; WAIT_L(0); MMA(1, 0, At, B0); BAR; SCHED;
	s_mov_b32 m0, s97
	v_lshl_add_u64 v[150:151], v[220:221], 0, s[22:23]
	global_load_lds_dwordx4 v[150:151], off
	v_lshl_add_u64 v[150:151], v[222:223], 0, s[22:23]
	s_mov_b32 m0, s89
	s_nop 0
	global_load_lds_dwordx4 v[150:151], off
	s_waitcnt vmcnt(6)
	s_barrier
	s_setprio 1
	v_mfma_f32_16x16x32_bf16 v[28:31], v[166:169], v[200:203], v[28:31]
	v_mfma_f32_16x16x32_bf16 v[24:27], v[166:169], v[208:211], v[24:27]
	v_mfma_f32_16x16x32_bf16 v[20:23], v[174:177], v[200:203], v[20:23]
	v_mfma_f32_16x16x32_bf16 v[16:19], v[174:177], v[208:211], v[16:19]
	v_mfma_f32_16x16x32_bf16 v[12:15], v[182:185], v[200:203], v[12:15]
	v_mfma_f32_16x16x32_bf16 v[8:11], v[182:185], v[208:211], v[8:11]
	v_mfma_f32_16x16x32_bf16 v[4:7], v[190:193], v[200:203], v[4:7]
	v_mfma_f32_16x16x32_bf16 v[0:3], v[190:193], v[208:211], v[0:3]
	v_mfma_f32_16x16x32_bf16 v[28:31], v[170:173], v[204:207], v[28:31]
	v_mfma_f32_16x16x32_bf16 v[24:27], v[170:173], v[212:215], v[24:27]
	v_mfma_f32_16x16x32_bf16 v[20:23], v[178:181], v[204:207], v[20:23]
	v_mfma_f32_16x16x32_bf16 v[16:19], v[178:181], v[212:215], v[16:19]
	v_mfma_f32_16x16x32_bf16 v[12:15], v[186:189], v[204:207], v[12:15]
	v_mfma_f32_16x16x32_bf16 v[8:11], v[186:189], v[212:215], v[8:11]
	v_mfma_f32_16x16x32_bf16 v[4:7], v[196:199], v[204:207], v[4:7]
	v_mfma_f32_16x16x32_bf16 v[0:3], v[196:199], v[212:215], v[0:3]
	s_setprio 0
	s_barrier
	ds_read_b128 v[150:153], v147
	ds_read_b128 v[154:157], v147 offset:1024
	ds_read_b128 v[158:161], v147 offset:2048
	ds_read_b128 v[162:165], v147 offset:3072
	s_mov_b32 m0, s88
	v_lshl_add_u64 v[200:201], v[216:217], 0, s[52:53]
	ds_read_b128 v[166:169], v145 offset:32768
	ds_read_b128 v[170:173], v145 offset:33792
	ds_read_b128 v[174:177], v143 offset:32768
	ds_read_b128 v[178:181], v143 offset:33792
	ds_read_b128 v[182:185], v142 offset:32768
	ds_read_b128 v[186:189], v142 offset:33792
	ds_read_b128 v[190:193], v141 offset:32768
	ds_read_b128 v[196:199], v141 offset:33792
	global_load_lds_dwordx4 v[200:201], off
	v_lshl_add_u64 v[200:201], v[218:219], 0, s[52:53]
	s_mov_b32 m0, s24
	s_nop 0
	global_load_lds_dwordx4 v[200:201], off
	s_waitcnt lgkmcnt(8)
	s_barrier
	s_waitcnt lgkmcnt(0)
	s_setprio 1
	s_waitcnt lgkmcnt(0)
	v_mfma_f32_16x16x32_bf16 v[124:127], v[166:169], v[150:153], v[124:127]
	v_mfma_f32_16x16x32_bf16 v[120:123], v[166:169], v[158:161], v[120:123]
	v_mfma_f32_16x16x32_bf16 v[116:119], v[174:177], v[150:153], v[116:119]
	v_mfma_f32_16x16x32_bf16 v[112:115], v[174:177], v[158:161], v[112:115]
	v_mfma_f32_16x16x32_bf16 v[108:111], v[182:185], v[150:153], v[108:111]
	v_mfma_f32_16x16x32_bf16 v[104:107], v[182:185], v[158:161], v[104:107]
	v_mfma_f32_16x16x32_bf16 v[100:103], v[190:193], v[150:153], v[100:103]
	v_mfma_f32_16x16x32_bf16 v[96:99], v[190:193], v[158:161], v[96:99]
	v_mfma_f32_16x16x32_bf16 v[124:127], v[170:173], v[154:157], v[124:127]
	v_mfma_f32_16x16x32_bf16 v[120:123], v[170:173], v[162:165], v[120:123]
	v_mfma_f32_16x16x32_bf16 v[116:119], v[178:181], v[154:157], v[116:119]
	v_mfma_f32_16x16x32_bf16 v[112:115], v[178:181], v[162:165], v[112:115]
	v_mfma_f32_16x16x32_bf16 v[108:111], v[186:189], v[154:157], v[108:111]
	v_mfma_f32_16x16x32_bf16 v[104:107], v[186:189], v[162:165], v[104:107]
	v_mfma_f32_16x16x32_bf16 v[100:103], v[196:199], v[154:157], v[100:103]
	v_mfma_f32_16x16x32_bf16 v[96:99], v[196:199], v[162:165], v[96:99]
	s_setprio 0
	s_barrier
	s_mov_b32 m0, s25
	v_lshl_add_u64 v[224:225], v[220:221], 0, s[56:57]
	ds_read_b128 v[200:203], v146
	ds_read_b128 v[204:207], v146 offset:1024
	ds_read_b128 v[208:211], v146 offset:2048
	ds_read_b128 v[212:215], v146 offset:3072
	global_load_lds_dwordx4 v[224:225], off
	v_lshl_add_u64 v[224:225], v[222:223], 0, s[56:57]
	s_mov_b32 m0, s78
	s_nop 0
	global_load_lds_dwordx4 v[224:225], off
	s_barrier
	s_waitcnt lgkmcnt(0)
	s_setprio 1
	s_waitcnt lgkmcnt(0)
	v_mfma_f32_16x16x32_bf16 v[92:95], v[166:169], v[200:203], v[92:95]
	v_mfma_f32_16x16x32_bf16 v[88:91], v[166:169], v[208:211], v[88:91]
	v_mfma_f32_16x16x32_bf16 v[84:87], v[174:177], v[200:203], v[84:87]
	v_mfma_f32_16x16x32_bf16 v[80:83], v[174:177], v[208:211], v[80:83]
	v_mfma_f32_16x16x32_bf16 v[76:79], v[182:185], v[200:203], v[76:79]
	v_mfma_f32_16x16x32_bf16 v[72:75], v[182:185], v[208:211], v[72:75]
	v_mfma_f32_16x16x32_bf16 v[68:71], v[190:193], v[200:203], v[68:71]
	v_mfma_f32_16x16x32_bf16 v[64:67], v[190:193], v[208:211], v[64:67]
	v_mfma_f32_16x16x32_bf16 v[92:95], v[170:173], v[204:207], v[92:95]
	v_mfma_f32_16x16x32_bf16 v[88:91], v[170:173], v[212:215], v[88:91]
	v_mfma_f32_16x16x32_bf16 v[84:87], v[178:181], v[204:207], v[84:87]
	v_mfma_f32_16x16x32_bf16 v[80:83], v[178:181], v[212:215], v[80:83]
	v_mfma_f32_16x16x32_bf16 v[76:79], v[186:189], v[204:207], v[76:79]
	v_mfma_f32_16x16x32_bf16 v[72:75], v[186:189], v[212:215], v[72:75]
	v_mfma_f32_16x16x32_bf16 v[68:71], v[196:199], v[204:207], v[68:71]
	v_mfma_f32_16x16x32_bf16 v[64:67], v[196:199], v[212:215], v[64:67]
	s_setprio 0
	s_mov_b32 m0, s79
	v_lshl_add_u64 v[216:217], v[216:217], 0, s[62:63]
	s_barrier
	ds_read_b128 v[166:169], v145 offset:49152
	ds_read_b128 v[170:173], v145 offset:50176
	ds_read_b128 v[174:177], v143 offset:49152
	ds_read_b128 v[178:181], v143 offset:50176
	ds_read_b128 v[182:185], v142 offset:49152
	ds_read_b128 v[186:189], v142 offset:50176
	ds_read_b128 v[190:193], v141 offset:49152
	ds_read_b128 v[196:199], v141 offset:50176
	global_load_lds_dwordx4 v[216:217], off
	v_lshl_add_u64 v[216:217], v[218:219], 0, s[62:63]
	s_mov_b32 m0, s80
	s_nop 0
	global_load_lds_dwordx4 v[216:217], off
	s_barrier
; #define WAIT_V(n) asm volatile("s_waitcnt vmcnt(" #n ")" ::: "memory")
; #define WAIT_L(n) asm volatile("s_waitcnt lgkmcnt(" #n ")" ::: "memory")
; #define BAR __builtin_amdgcn_s_barrier()
; #define SCHED __builtin_amdgcn_sched_barrier(0)
; __device__ __forceinline__ void gemm_tile(const u16* __restrict__ A, const u16* __restrict__ Bt, const int K,
;                                           const int brow, const int bcol, f32x4 (&acc)[2][2][4][2],
;                                           const bool ZERO_INIT = true) {
;     ...
;     LDA(At, 1, 1); STAGE(SA(1, 0), A, brow, t + 3);
;     BAR; WAIT_L(0); MMA(1, 0, At, B0); BAR; SCHED;
;     STAGE(SB(1, 1), Bt, bcol + HALF, t + 3);
;     WAIT_V(6); BAR; MMA(1, 1, At, B1); BAR;
;   }
;   { LDB(B0, 0, 0); LDA(At, 0, 0); STAGE(SA(1, 1), A, brow + HALF, nt - 1);
;     BAR; WAIT_L(0); MMA(0, 0, At, B0); BAR;
;     LDB(B1, 0, 1); BAR; WAIT_L(0); MMA(0, 1, At, B1); BAR;
	s_waitcnt lgkmcnt(0)
	s_setprio 1
	s_waitcnt lgkmcnt(0)
	v_mfma_f32_16x16x32_bf16 v[60:63], v[166:169], v[150:153], v[60:63]
	v_mfma_f32_16x16x32_bf16 v[56:59], v[166:169], v[158:161], v[56:59]
	v_mfma_f32_16x16x32_bf16 v[52:55], v[174:177], v[150:153], v[52:55]
	v_mfma_f32_16x16x32_bf16 v[48:51], v[174:177], v[158:161], v[48:51]
	v_mfma_f32_16x16x32_bf16 v[44:47], v[182:185], v[150:153], v[44:47]
	v_mfma_f32_16x16x32_bf16 v[40:43], v[182:185], v[158:161], v[40:43]
	v_mfma_f32_16x16x32_bf16 v[36:39], v[190:193], v[150:153], v[36:39]
	v_mfma_f32_16x16x32_bf16 v[32:35], v[190:193], v[158:161], v[32:35]
	v_mfma_f32_16x16x32_bf16 v[60:63], v[170:173], v[154:157], v[60:63]
	v_mfma_f32_16x16x32_bf16 v[56:59], v[170:173], v[162:165], v[56:59]
	v_mfma_f32_16x16x32_bf16 v[52:55], v[178:181], v[154:157], v[52:55]
	v_mfma_f32_16x16x32_bf16 v[48:51], v[178:181], v[162:165], v[48:51]
	v_mfma_f32_16x16x32_bf16 v[44:47], v[186:189], v[154:157], v[44:47]
	v_mfma_f32_16x16x32_bf16 v[40:43], v[186:189], v[162:165], v[40:43]
	v_mfma_f32_16x16x32_bf16 v[36:39], v[196:199], v[154:157], v[36:39]
	v_mfma_f32_16x16x32_bf16 v[32:35], v[196:199], v[162:165], v[32:35]
	s_setprio 0
	s_barrier
	s_mov_b32 m0, s81
	v_lshl_add_u64 v[150:151], v[220:221], 0, s[64:65]
	global_load_lds_dwordx4 v[150:151], off
	v_lshl_add_u64 v[150:151], v[222:223], 0, s[64:65]
	s_mov_b32 m0, s82
	s_nop 0
	global_load_lds_dwordx4 v[150:151], off
	s_waitcnt vmcnt(6)
	s_barrier
	s_setprio 1
	v_mfma_f32_16x16x32_bf16 v[28:31], v[166:169], v[200:203], v[28:31]
	v_mfma_f32_16x16x32_bf16 v[24:27], v[166:169], v[208:211], v[24:27]
	v_mfma_f32_16x16x32_bf16 v[20:23], v[174:177], v[200:203], v[20:23]
	v_mfma_f32_16x16x32_bf16 v[16:19], v[174:177], v[208:211], v[16:19]
	v_mfma_f32_16x16x32_bf16 v[12:15], v[182:185], v[200:203], v[12:15]
	v_mfma_f32_16x16x32_bf16 v[8:11], v[182:185], v[208:211], v[8:11]
	v_mfma_f32_16x16x32_bf16 v[4:7], v[190:193], v[200:203], v[4:7]
	v_mfma_f32_16x16x32_bf16 v[0:3], v[190:193], v[208:211], v[0:3]
	v_mfma_f32_16x16x32_bf16 v[28:31], v[170:173], v[204:207], v[28:31]
	v_mfma_f32_16x16x32_bf16 v[24:27], v[170:173], v[212:215], v[24:27]
	v_mfma_f32_16x16x32_bf16 v[20:23], v[178:181], v[204:207], v[20:23]
	v_mfma_f32_16x16x32_bf16 v[16:19], v[178:181], v[212:215], v[16:19]
	v_mfma_f32_16x16x32_bf16 v[12:15], v[186:189], v[204:207], v[12:15]
	v_mfma_f32_16x16x32_bf16 v[8:11], v[186:189], v[212:215], v[8:11]
	v_mfma_f32_16x16x32_bf16 v[4:7], v[196:199], v[204:207], v[4:7]
	v_mfma_f32_16x16x32_bf16 v[0:3], v[196:199], v[212:215], v[0:3]
	s_setprio 0
	s_add_i32 s77, s77, 2
	s_add_u32 s70, s70, 0x100
	s_addc_u32 s71, s71, 0
	s_cmp_lt_u32 s77, 28
	s_barrier
	s_cbranch_scc1 .LBB0_164
	s_add_u32 s24, s91, s66
	s_addc_u32 s25, s92, s67
	s_mov_b32 m0, s83
	v_lshl_add_u64 v[190:191], s[24:25], 0, v[128:129]
	ds_read_b128 v[132:135], v149
	ds_read_b128 v[136:139], v149 offset:1024
	ds_read_b128 v[150:153], v149 offset:2048
	ds_read_b128 v[154:157], v149 offset:3072
	ds_read_b128 v[158:161], v145
	ds_read_b128 v[162:165], v145 offset:1024
	ds_read_b128 v[166:169], v143
	ds_read_b128 v[170:173], v143 offset:1024
	ds_read_b128 v[174:177], v142
	ds_read_b128 v[178:181], v142 offset:1024
	ds_read_b128 v[182:185], v141
	ds_read_b128 v[186:189], v141 offset:1024
	global_load_lds_dwordx4 v[190:191], off
	v_lshl_add_u64 v[130:131], s[24:25], 0, v[130:131]
	s_mov_b32 m0, s76
	s_nop 0
	global_load_lds_dwordx4 v[130:131], off
	s_barrier
	s_waitcnt lgkmcnt(0)
	s_setprio 1
	s_waitcnt lgkmcnt(0)
	v_mfma_f32_16x16x32_bf16 v[124:127], v[158:161], v[132:135], v[124:127]
	v_mfma_f32_16x16x32_bf16 v[120:123], v[158:161], v[150:153], v[120:123]
	v_mfma_f32_16x16x32_bf16 v[116:119], v[166:169], v[132:135], v[116:119]
	v_mfma_f32_16x16x32_bf16 v[112:115], v[166:169], v[150:153], v[112:115]
	v_mfma_f32_16x16x32_bf16 v[108:111], v[174:177], v[132:135], v[108:111]
	v_mfma_f32_16x16x32_bf16 v[104:107], v[174:177], v[150:153], v[104:107]
	v_mfma_f32_16x16x32_bf16 v[100:103], v[182:185], v[132:135], v[100:103]
	v_mfma_f32_16x16x32_bf16 v[96:99], v[182:185], v[150:153], v[96:99]
	v_mfma_f32_16x16x32_bf16 v[124:127], v[162:165], v[136:139], v[124:127]
	v_mfma_f32_16x16x32_bf16 v[120:123], v[162:165], v[154:157], v[120:123]
	v_mfma_f32_16x16x32_bf16 v[116:119], v[170:173], v[136:139], v[116:119]
	v_mfma_f32_16x16x32_bf16 v[112:115], v[170:173], v[154:157], v[112:115]
	v_mfma_f32_16x16x32_bf16 v[108:111], v[178:181], v[136:139], v[108:111]
	v_mfma_f32_16x16x32_bf16 v[104:107], v[178:181], v[154:157], v[104:107]
	v_mfma_f32_16x16x32_bf16 v[100:103], v[186:189], v[136:139], v[100:103]
	v_mfma_f32_16x16x32_bf16 v[96:99], v[186:189], v[154:157], v[96:99]
	s_setprio 0
	s_barrier
	ds_read_b128 v[190:193], v148
	ds_read_b128 v[196:199], v148 offset:1024
	ds_read_b128 v[200:203], v148 offset:2048
	ds_read_b128 v[204:207], v148 offset:3072
	s_barrier
	s_waitcnt lgkmcnt(0)
	s_setprio 1
	s_waitcnt lgkmcnt(0)
	v_mfma_f32_16x16x32_bf16 v[76:79], v[174:177], v[190:193], v[76:79]
	v_mfma_f32_16x16x32_bf16 v[72:75], v[174:177], v[200:203], v[72:75]
	v_mfma_f32_16x16x32_bf16 v[68:71], v[182:185], v[190:193], v[68:71]
	v_mfma_f32_16x16x32_bf16 v[64:67], v[182:185], v[200:203], v[64:67]
	v_mfma_f32_16x16x32_bf16 v[92:95], v[158:161], v[190:193], v[92:95]
	v_mfma_f32_16x16x32_bf16 v[88:91], v[158:161], v[200:203], v[88:91]
	v_mfma_f32_16x16x32_bf16 v[84:87], v[166:169], v[190:193], v[84:87]
	v_mfma_f32_16x16x32_bf16 v[80:83], v[166:169], v[200:203], v[80:83]
	v_mfma_f32_16x16x32_bf16 v[76:79], v[178:181], v[196:199], v[76:79]
	v_mfma_f32_16x16x32_bf16 v[72:75], v[178:181], v[204:207], v[72:75]
	v_mfma_f32_16x16x32_bf16 v[68:71], v[186:189], v[196:199], v[68:71]
	v_mfma_f32_16x16x32_bf16 v[64:67], v[186:189], v[204:207], v[64:67]
	v_mfma_f32_16x16x32_bf16 v[208:211], v[162:165], v[196:199], v[92:95]
	v_mfma_f32_16x16x32_bf16 v[158:161], v[162:165], v[204:207], v[88:91]
	v_mfma_f32_16x16x32_bf16 v[162:165], v[170:173], v[196:199], v[84:87]
	v_mfma_f32_16x16x32_bf16 v[166:169], v[170:173], v[204:207], v[80:83]
	s_setprio 0
	s_barrier
; #define WAIT_V(n) asm volatile("s_waitcnt vmcnt(" #n ")" ::: "memory")
; #define WAIT_L(n) asm volatile("s_waitcnt lgkmcnt(" #n ")" ::: "memory")
; #define BAR __builtin_amdgcn_s_barrier()
; __device__ __forceinline__ void gemm_tile(const u16* __restrict__ A, const u16* __restrict__ Bt, const int K,
;                                           const int brow, const int bcol, f32x4 (&acc)[2][2][4][2],
;                                           const bool ZERO_INIT = true) {
;     ...
;     LDA(At, 0, 1); WAIT_V(4); BAR; WAIT_L(0); MMA(1, 0, At, B0); MMA(1, 1, At, B1); BAR; }
;   { LDB(B0, 1, 0); LDA(At, 1, 0); WAIT_V(2); BAR; WAIT_L(0); MMA(0, 0, At, B0); BAR;
;     LDB(B1, 1, 1); WAIT_V(0); BAR; WAIT_L(0); MMA(0, 1, At, B1); BAR;
	s_nop 0
	ds_read_b128 v[80:83], v145 offset:16384
	ds_read_b128 v[84:87], v145 offset:17408
	ds_read_b128 v[88:91], v143 offset:16384
	ds_read_b128 v[92:95], v143 offset:17408
	ds_read_b128 v[170:173], v142 offset:16384
	ds_read_b128 v[174:177], v142 offset:17408
	ds_read_b128 v[178:181], v141 offset:16384
	ds_read_b128 v[182:185], v141 offset:17408
	s_waitcnt vmcnt(4)
	s_barrier
	s_waitcnt lgkmcnt(0)
	s_setprio 1
	s_waitcnt lgkmcnt(0)
	v_mfma_f32_16x16x32_bf16 v[44:47], v[170:173], v[132:135], v[44:47]
	v_mfma_f32_16x16x32_bf16 v[40:43], v[170:173], v[150:153], v[40:43]
	v_mfma_f32_16x16x32_bf16 v[36:39], v[178:181], v[132:135], v[36:39]
	v_mfma_f32_16x16x32_bf16 v[32:35], v[178:181], v[150:153], v[32:35]
	v_mfma_f32_16x16x32_bf16 v[60:63], v[80:83], v[132:135], v[60:63]
	v_mfma_f32_16x16x32_bf16 v[56:59], v[80:83], v[150:153], v[56:59]
	v_mfma_f32_16x16x32_bf16 v[52:55], v[88:91], v[132:135], v[52:55]
	v_mfma_f32_16x16x32_bf16 v[48:51], v[88:91], v[150:153], v[48:51]
	v_mfma_f32_16x16x32_bf16 v[44:47], v[174:177], v[136:139], v[44:47]
	v_mfma_f32_16x16x32_bf16 v[40:43], v[174:177], v[154:157], v[40:43]
	v_mfma_f32_16x16x32_bf16 v[36:39], v[182:185], v[136:139], v[36:39]
	v_mfma_f32_16x16x32_bf16 v[32:35], v[182:185], v[154:157], v[32:35]
	v_mfma_f32_16x16x32_bf16 v[186:189], v[84:87], v[136:139], v[60:63]
	v_mfma_f32_16x16x32_bf16 v[212:215], v[84:87], v[154:157], v[56:59]
	v_mfma_f32_16x16x32_bf16 v[216:219], v[92:95], v[136:139], v[52:55]
	v_mfma_f32_16x16x32_bf16 v[220:223], v[92:95], v[154:157], v[48:51]
	s_setprio 0
	s_setprio 1
	v_mfma_f32_16x16x32_bf16 v[0:3], v[178:181], v[200:203], v[0:3]
	v_mfma_f32_16x16x32_bf16 v[28:31], v[80:83], v[190:193], v[28:31]
	v_mfma_f32_16x16x32_bf16 v[24:27], v[80:83], v[200:203], v[24:27]
	v_mfma_f32_16x16x32_bf16 v[20:23], v[88:91], v[190:193], v[20:23]
	v_mfma_f32_16x16x32_bf16 v[16:19], v[88:91], v[200:203], v[16:19]
	v_mfma_f32_16x16x32_bf16 v[12:15], v[170:173], v[190:193], v[12:15]
	v_mfma_f32_16x16x32_bf16 v[8:11], v[170:173], v[200:203], v[8:11]
	v_mfma_f32_16x16x32_bf16 v[4:7], v[178:181], v[190:193], v[4:7]
	v_mfma_f32_16x16x32_bf16 v[0:3], v[182:185], v[204:207], v[0:3]
	v_mfma_f32_16x16x32_bf16 v[130:133], v[84:87], v[196:199], v[28:31]
	v_mfma_f32_16x16x32_bf16 v[134:137], v[84:87], v[204:207], v[24:27]
	v_mfma_f32_16x16x32_bf16 v[148:151], v[92:95], v[196:199], v[20:23]
	v_mfma_f32_16x16x32_bf16 v[152:155], v[92:95], v[204:207], v[16:19]
	v_mfma_f32_16x16x32_bf16 v[224:227], v[174:177], v[196:199], v[12:15]
	v_mfma_f32_16x16x32_bf16 v[170:173], v[174:177], v[204:207], v[8:11]
	v_mfma_f32_16x16x32_bf16 v[174:177], v[182:185], v[196:199], v[4:7]
	s_setprio 0
	s_barrier
	s_nop 0
	ds_read_b128 v[4:7], v147
	ds_read_b128 v[8:11], v147 offset:1024
	ds_read_b128 v[12:15], v147 offset:2048
	ds_read_b128 v[178:181], v147 offset:3072
	ds_read_b128 v[16:19], v145 offset:32768
	ds_read_b128 v[20:23], v145 offset:33792
	ds_read_b128 v[24:27], v143 offset:32768
	ds_read_b128 v[48:51], v143 offset:33792
	ds_read_b128 v[182:185], v142 offset:32768
	ds_read_b128 v[190:193], v142 offset:33792
	ds_read_b128 v[196:199], v141 offset:32768
	ds_read_b128 v[200:203], v141 offset:33792
	s_waitcnt vmcnt(2)
	s_barrier
	s_waitcnt lgkmcnt(0)
	s_setprio 1
	s_waitcnt lgkmcnt(0)
	v_mfma_f32_16x16x32_bf16 v[28:31], v[16:19], v[4:7], v[124:127]
	v_mfma_f32_16x16x32_bf16 v[124:127], v[20:23], v[8:11], v[28:31]
	v_mfma_f32_16x16x32_bf16 v[28:31], v[16:19], v[12:15], v[120:123]
	v_mfma_f32_16x16x32_bf16 v[92:95], v[20:23], v[178:181], v[28:31]
	v_mfma_f32_16x16x32_bf16 v[28:31], v[24:27], v[4:7], v[116:119]
	v_mfma_f32_16x16x32_bf16 v[120:123], v[48:51], v[8:11], v[28:31]
	v_mfma_f32_16x16x32_bf16 v[28:31], v[24:27], v[12:15], v[112:115]
	v_mfma_f32_16x16x32_bf16 v[88:91], v[48:51], v[178:181], v[28:31]
	v_mfma_f32_16x16x32_bf16 v[28:31], v[182:185], v[4:7], v[108:111]
	v_mfma_f32_16x16x32_bf16 v[116:119], v[190:193], v[8:11], v[28:31]
	v_mfma_f32_16x16x32_bf16 v[28:31], v[182:185], v[12:15], v[104:107]
	v_mfma_f32_16x16x32_bf16 v[84:87], v[190:193], v[178:181], v[28:31]
	v_mfma_f32_16x16x32_bf16 v[28:31], v[196:199], v[4:7], v[100:103]
	v_mfma_f32_16x16x32_bf16 v[112:115], v[200:203], v[8:11], v[28:31]
	v_mfma_f32_16x16x32_bf16 v[28:31], v[196:199], v[12:15], v[96:99]
	v_mfma_f32_16x16x32_bf16 v[80:83], v[200:203], v[178:181], v[28:31]
	s_setprio 0
	s_barrier
; #define WAIT_V(n) asm volatile("s_waitcnt vmcnt(" #n ")" ::: "memory")
; #define WAIT_L(n) asm volatile("s_waitcnt lgkmcnt(" #n ")" ::: "memory")
; #define BAR __builtin_amdgcn_s_barrier()
; __device__ __forceinline__ void gemm_tile(const u16* __restrict__ A, const u16* __restrict__ Bt, const int K,
;                                           const int brow, const int bcol, f32x4 (&acc)[2][2][4][2],
;                                           const bool ZERO_INIT = true) {
;     ...
;   { LDB(B0, 1, 0); LDA(At, 1, 0); WAIT_V(2); BAR; WAIT_L(0); MMA(0, 0, At, B0); BAR;
;     LDB(B1, 1, 1); WAIT_V(0); BAR; WAIT_L(0); MMA(0, 1, At, B1); BAR;
;     LDA(At, 1, 1); BAR; WAIT_L(0); MMA(1, 0, At, B0); MMA(1, 1, At, B1); BAR; }
;   if (wr == 0) BAR;
; __device__ void phase1(const Params& p) {
;     ...
;         const int t = EPI_T(bj, n);
;         const float r = rs[t];
	ds_read_b128 v[204:207], v146
	ds_read_b128 v[228:231], v146 offset:1024
	ds_read_b128 v[232:235], v146 offset:2048
	ds_read_b128 v[236:239], v146 offset:3072
	s_waitcnt vmcnt(0)
	v_lshrrev_b32_e32 v244, 1, v194
	v_and_b32_e32 v245, 15, v194
	v_and_b32_e32 v244, 0x60, v244
	v_add3_u32 v244, s72, v245, v244
	v_lshlrev_b32_e32 v244, 2, v244
	global_load_dword v240, v244, s[30:31]
	global_load_dword v241, v244, s[30:31] offset:64
	global_load_dword v242, v244, s[30:31] offset:512
	global_load_dword v243, v244, s[30:31] offset:576
	s_barrier
	s_waitcnt lgkmcnt(0)
	s_setprio 1
	s_waitcnt lgkmcnt(0)
	v_mfma_f32_16x16x32_bf16 v[28:31], v[16:19], v[204:207], v[208:211]
	v_mfma_f32_16x16x32_bf16 v[16:19], v[16:19], v[232:235], v[158:161]
	v_mfma_f32_16x16x32_bf16 v[60:63], v[20:23], v[228:231], v[28:31]
	v_mfma_f32_16x16x32_bf16 v[28:31], v[20:23], v[236:239], v[16:19]
	v_mfma_f32_16x16x32_bf16 v[16:19], v[24:27], v[204:207], v[162:165]
	v_mfma_f32_16x16x32_bf16 v[56:59], v[48:51], v[228:231], v[16:19]
	v_mfma_f32_16x16x32_bf16 v[16:19], v[24:27], v[232:235], v[166:169]
	v_mfma_f32_16x16x32_bf16 v[24:27], v[48:51], v[236:239], v[16:19]
	v_mfma_f32_16x16x32_bf16 v[16:19], v[182:185], v[204:207], v[76:79]
	v_mfma_f32_16x16x32_bf16 v[52:55], v[190:193], v[228:231], v[16:19]
	v_mfma_f32_16x16x32_bf16 v[16:19], v[182:185], v[232:235], v[72:75]
	v_mfma_f32_16x16x32_bf16 v[20:23], v[190:193], v[236:239], v[16:19]
	v_mfma_f32_16x16x32_bf16 v[16:19], v[196:199], v[204:207], v[68:71]
	v_mfma_f32_16x16x32_bf16 v[48:51], v[200:203], v[228:231], v[16:19]
	v_mfma_f32_16x16x32_bf16 v[16:19], v[196:199], v[232:235], v[64:67]
	v_mfma_f32_16x16x32_bf16 v[16:19], v[200:203], v[236:239], v[16:19]
	s_setprio 0
	s_barrier
	ds_read_b128 v[156:159], v145 offset:49152
	ds_read_b128 v[160:163], v145 offset:50176
	ds_read_b128 v[164:167], v143 offset:49152
	ds_read_b128 v[182:185], v143 offset:50176
	ds_read_b128 v[190:193], v142 offset:49152
	ds_read_b128 v[196:199], v142 offset:50176
	ds_read_b128 v[200:203], v141 offset:49152
	ds_read_b128 v[208:211], v141 offset:50176
	s_barrier
	s_waitcnt lgkmcnt(0)
	s_setprio 1
	s_waitcnt lgkmcnt(0)
	v_mfma_f32_16x16x32_bf16 v[64:67], v[156:159], v[4:7], v[186:189]
	v_mfma_f32_16x16x32_bf16 v[108:111], v[160:163], v[8:11], v[64:67]
	v_mfma_f32_16x16x32_bf16 v[64:67], v[156:159], v[12:15], v[212:215]
	v_mfma_f32_16x16x32_bf16 v[76:79], v[160:163], v[178:181], v[64:67]
	v_mfma_f32_16x16x32_bf16 v[64:67], v[164:167], v[4:7], v[216:219]
	v_mfma_f32_16x16x32_bf16 v[44:47], v[190:193], v[4:7], v[44:47]
	v_mfma_f32_16x16x32_bf16 v[4:7], v[200:203], v[4:7], v[36:39]
	v_mfma_f32_16x16x32_bf16 v[104:107], v[182:185], v[8:11], v[64:67]
	v_mfma_f32_16x16x32_bf16 v[64:67], v[164:167], v[12:15], v[220:223]
	v_mfma_f32_16x16x32_bf16 v[40:43], v[190:193], v[12:15], v[40:43]
	v_mfma_f32_16x16x32_bf16 v[96:99], v[208:211], v[8:11], v[4:7]
	v_mfma_f32_16x16x32_bf16 v[4:7], v[200:203], v[12:15], v[32:35]
	v_mfma_f32_16x16x32_bf16 v[72:75], v[182:185], v[178:181], v[64:67]
	v_mfma_f32_16x16x32_bf16 v[100:103], v[196:199], v[8:11], v[44:47]
	v_mfma_f32_16x16x32_bf16 v[68:71], v[196:199], v[178:181], v[40:43]
	v_mfma_f32_16x16x32_bf16 v[64:67], v[208:211], v[178:181], v[4:7]
	s_setprio 0
	s_setprio 1
	v_mfma_f32_16x16x32_bf16 v[4:7], v[156:159], v[204:207], v[130:133]
	v_mfma_f32_16x16x32_bf16 v[44:47], v[160:163], v[228:231], v[4:7]
	v_mfma_f32_16x16x32_bf16 v[4:7], v[156:159], v[232:235], v[134:137]
	v_mfma_f32_16x16x32_bf16 v[12:15], v[160:163], v[236:239], v[4:7]
	v_mfma_f32_16x16x32_bf16 v[4:7], v[164:167], v[204:207], v[148:151]
	v_mfma_f32_16x16x32_bf16 v[40:43], v[182:185], v[228:231], v[4:7]
	v_mfma_f32_16x16x32_bf16 v[4:7], v[164:167], v[232:235], v[152:155]
	v_mfma_f32_16x16x32_bf16 v[8:11], v[182:185], v[236:239], v[4:7]
	v_mfma_f32_16x16x32_bf16 v[4:7], v[190:193], v[204:207], v[224:227]
	v_mfma_f32_16x16x32_bf16 v[36:39], v[196:199], v[228:231], v[4:7]
	v_mfma_f32_16x16x32_bf16 v[4:7], v[190:193], v[232:235], v[170:173]
	v_mfma_f32_16x16x32_bf16 v[32:35], v[200:203], v[204:207], v[174:177]
	v_mfma_f32_16x16x32_bf16 v[0:3], v[200:203], v[232:235], v[0:3]
	v_mfma_f32_16x16x32_bf16 v[4:7], v[196:199], v[236:239], v[4:7]
	v_mfma_f32_16x16x32_bf16 v[32:35], v[208:211], v[228:231], v[32:35]
	v_mfma_f32_16x16x32_bf16 v[0:3], v[208:211], v[236:239], v[0:3]
	s_setprio 0
	s_movk_i32 s7, 0x100
	v_cmp_gt_u32_e32 vcc, s7, v140
	s_barrier
	s_and_saveexec_b64 s[66:67], vcc
	s_cbranch_execz .LBB0_167
	s_barrier

; __device__ void phase1(const Params& p) {
;     ...
;         const int t = EPI_T(bj, n);
;         const float r = rs[t];
;         u16* drow = dst + (size_t)t * ld - cofs;
;         #pragma unroll
;         for (int ai = 0; ai < 2; ++ai)
;           #pragma unroll
;           for (int m = 0; m < 4; ++m) {
;             float v[4];
;             #pragma unroll
;             for (int j = 0; j < 4; ++j) {
;               v[j] = acc[ai][bj][m][n][j] * r;
;               if (act == 2) v[j] = sigm(v[j]);
;             }
;             if (act == 2) {
;               *reinterpret_cast<unsigned*>(reinterpret_cast<unsigned char*>(dst) + (size_t)t * 2048 + (EPI_F(ai, m) - cofs)) =
;                   pk4_u8(v[0], v[1], v[2], v[3]);
;             } else {
;               v2u o; o.x = pk2(v[0], v[1]); o.y = pk2(v[2], v[3]);
;               *reinterpret_cast<v2u*>(drow + EPI_F(ai, m)) = o;
.LBB0_177:
	v_lshrrev_b32_e32 v131, 1, v128
	v_and_b32_e32 v130, 15, v128
	v_and_b32_e32 v131, 0x60, v131
	v_add3_u32 v132, s72, v130, v131
	v_ashrrev_i32_e32 v133, 31, v132
	v_lshl_add_u64 v[134:135], v[132:133], 2, s[30:31]
	s_xor_b64 s[76:77], s[76:77], -1
	s_lshl_b32 s24, s7, 1
	v_ashrrev_i32_e32 v130, 2, v128
	v_lshrrev_b32_e32 v128, 2, v128
	s_sub_u32 s72, s66, s24
	v_and_b32_e32 v130, 0xffffffc0, v130
	v_and_b32_e32 v128, 12, v128
	s_subb_u32 s73, s67, 0
	v_mad_i64_i32 v[138:139], s[24:25], s70, v132, 0
	s_mov_b64 s[78:79], -1
	v_add3_u32 v130, v130, s6, v128
	s_and_b64 vcc, exec, s[76:77]
	v_lshl_add_u64 v[138:139], v[138:139], 1, s[72:73]
	s_waitcnt vmcnt(0)
	v_mov_b32_e32 v136, v240
	v_pk_mul_f32 v[140:141], v[124:125], v[136:137] op_sel_hi:[1,0]
	v_pk_mul_f32 v[142:143], v[126:127], v[136:137] op_sel_hi:[1,0]
	s_cbranch_vccz .LBB0_179
	v_ashrrev_i32_e32 v131, 31, v130
	v_cvt_pk_bf16_f32 v124, v140, v141
	v_cvt_pk_bf16_f32 v125, v142, v143
	v_lshl_add_u64 v[126:127], v[130:131], 1, v[138:139]
	global_store_dwordx2 v[126:127], v[124:125], off
	s_mov_b64 s[78:79], 0

; __device__ void phase1(const Params& p) {
;     ...
;         const int t = EPI_T(bj, n);
;         const float r = rs[t];
;         u16* drow = dst + (size_t)t * ld - cofs;
;         #pragma unroll
;         for (int ai = 0; ai < 2; ++ai)
;           #pragma unroll
;           for (int m = 0; m < 4; ++m) {
;             float v[4];
;             #pragma unroll
;             for (int j = 0; j < 4; ++j) {
;               v[j] = acc[ai][bj][m][n][j] * r;
;               if (act == 2) v[j] = sigm(v[j]);
;             }
;             if (act == 2) {
;               *reinterpret_cast<unsigned*>(reinterpret_cast<unsigned char*>(dst) + (size_t)t * 2048 + (EPI_F(ai, m) - cofs)) =
;                   pk4_u8(v[0], v[1], v[2], v[3]);
;             } else {
;               v2u o; o.x = pk2(v[0], v[1]); o.y = pk2(v[2], v[3]);
;               *reinterpret_cast<v2u*>(drow + EPI_F(ai, m)) = o;
.LBB0_209:
	v_mov_b32_e32 v98, v241
	v_add_u32_e32 v102, 16, v132
	v_mad_i64_i32 v[96:97], s[24:25], s70, v102, 0
	s_and_b64 vcc, exec, s[6:7]
	v_lshl_add_u64 v[96:97], v[96:97], 1, s[72:73]
	s_mov_b64 s[76:77], -1
	v_pk_mul_f32 v[100:101], v[92:93], v[98:99] op_sel_hi:[1,0]
	v_pk_mul_f32 v[94:95], v[94:95], v[98:99] op_sel_hi:[1,0]
	s_cbranch_vccnz .LBB0_211
	v_ashrrev_i32_e32 v131, 31, v130
	v_cvt_pk_bf16_f32 v92, v100, v101
	v_cvt_pk_bf16_f32 v93, v94, v95
	v_lshl_add_u64 v[104:105], v[130:131], 1, v[96:97]
	s_mov_b64 s[76:77], 0
	global_store_dwordx2 v[104:105], v[92:93], off

; __device__ void phase1(const Params& p) {
;     ...
;         const int t = EPI_T(bj, n);
;         const float r = rs[t];
;         u16* drow = dst + (size_t)t * ld - cofs;
;         #pragma unroll
;         for (int ai = 0; ai < 2; ++ai)
;           #pragma unroll
;           for (int m = 0; m < 4; ++m) {
;             float v[4];
;             #pragma unroll
;             for (int j = 0; j < 4; ++j) {
;               v[j] = acc[ai][bj][m][n][j] * r;
;               if (act == 2) v[j] = sigm(v[j]);
;             }
;             if (act == 2) {
;               *reinterpret_cast<unsigned*>(reinterpret_cast<unsigned char*>(dst) + (size_t)t * 2048 + (EPI_F(ai, m) - cofs)) =
;                   pk4_u8(v[0], v[1], v[2], v[3]);
;             } else {
;               v2u o; o.x = pk2(v[0], v[1]); o.y = pk2(v[2], v[3]);
;               *reinterpret_cast<v2u*>(drow + EPI_F(ai, m)) = o;
.LBB0_241:
	v_mov_b32_e32 v66, v242
	v_add_u32_e32 v70, 0x80, v132
	v_mad_i64_i32 v[64:65], s[24:25], s70, v70, 0
	s_and_b64 vcc, exec, s[6:7]
	v_lshl_add_u64 v[64:65], v[64:65], 1, s[72:73]
	s_mov_b64 s[76:77], -1
	v_pk_mul_f32 v[68:69], v[60:61], v[66:67] op_sel_hi:[1,0]
	v_pk_mul_f32 v[62:63], v[62:63], v[66:67] op_sel_hi:[1,0]
	s_cbranch_vccnz .LBB0_243
	v_ashrrev_i32_e32 v131, 31, v130
	v_cvt_pk_bf16_f32 v60, v68, v69
	v_cvt_pk_bf16_f32 v61, v62, v63
	v_lshl_add_u64 v[72:73], v[130:131], 1, v[64:65]
	s_mov_b64 s[76:77], 0
	global_store_dwordx2 v[72:73], v[60:61], off

; __device__ void phase1(const Params& p) {
;     ...
;         const int t = EPI_T(bj, n);
;         const float r = rs[t];
;         u16* drow = dst + (size_t)t * ld - cofs;
;         #pragma unroll
;         for (int ai = 0; ai < 2; ++ai)
;           #pragma unroll
;           for (int m = 0; m < 4; ++m) {
;             float v[4];
;             #pragma unroll
;             for (int j = 0; j < 4; ++j) {
;               v[j] = acc[ai][bj][m][n][j] * r;
;               if (act == 2) v[j] = sigm(v[j]);
;             }
;             if (act == 2) {
;               *reinterpret_cast<unsigned*>(reinterpret_cast<unsigned char*>(dst) + (size_t)t * 2048 + (EPI_F(ai, m) - cofs)) =
;                   pk4_u8(v[0], v[1], v[2], v[3]);
;             } else {
;               v2u o; o.x = pk2(v[0], v[1]); o.y = pk2(v[2], v[3]);
;               *reinterpret_cast<v2u*>(drow + EPI_F(ai, m)) = o;
.LBB0_273:
	v_mov_b32_e32 v34, v243
	v_add_u32_e32 v38, 0x90, v132
	v_mad_i64_i32 v[32:33], s[24:25], s70, v38, 0
	s_and_b64 vcc, exec, s[6:7]
	v_lshl_add_u64 v[32:33], v[32:33], 1, s[72:73]
	s_mov_b64 s[70:71], -1
	v_pk_mul_f32 v[36:37], v[28:29], v[34:35] op_sel_hi:[1,0]
	v_pk_mul_f32 v[30:31], v[30:31], v[34:35] op_sel_hi:[1,0]
	s_cbranch_vccnz .LBB0_275
	v_ashrrev_i32_e32 v131, 31, v130
	v_cvt_pk_bf16_f32 v28, v36, v37
	v_cvt_pk_bf16_f32 v29, v30, v31
	v_lshl_add_u64 v[40:41], v[130:131], 1, v[32:33]
	s_mov_b64 s[70:71], 0
	global_store_dwordx2 v[40:41], v[28:29], off
